# v61 + progress-flag publishes no longer write one LDS word from all 64 lanes (lane 0 writes the flag, other lanes distinct dummy words)
# baseline (speedup 1.0000x reference)
.LBB0_721:
	s_and_b64 s[8:9], s[0:1], exec
	v_readlane_b32 s8, v255, 9
	v_and_b32_e32 v166, 63, v44
	v_readlane_b32 s9, v255, 10
	v_and_b32_e32 v26, 31, v44
	v_lshlrev_b32_e32 v27, 6, v44
	s_cselect_b32 s27, s72, s9
	s_cselect_b32 s26, s39, s8
	s_mov_b64 s[8:9], -1
	s_cmp_lt_i32 s20, 4
	v_lshl_add_u32 v118, v45, 4, 0
	v_lshl_or_b32 v164, s42, 6, v166
	v_and_b32_e32 v119, 0x600, v27
	v_and_b32_e32 v123, 0x100, v27
	v_and_b32_e32 v129, 0xc0, v27
	v_lshlrev_b32_e32 v116, 2, v26
	s_waitcnt lgkmcnt(0)
	s_barrier
	s_cbranch_scc1 .LBB0_831
	v_lshl_or_b32 v167, s42, 2, v165
	s_mul_i32 s8, s42, 0x2100
	v_mov_b32_e32 v121, s7
	v_or_b32_e32 v120, s6, v46
	v_mad_u64_u32 v[124:125], s[6:7], v167, s69, v[118:119]
	s_add_i32 s8, s8, 0
	s_ashr_i32 s23, s22, 31
	v_lshlrev_b32_e32 v26, 2, v44
	v_lshrrev_b32_e32 v125, 5, v164
	s_add_i32 s15, s8, 0x1b000
	v_and_b32_e32 v122, 28, v26
	v_lshlrev_b32_e32 v26, 11, v125
	s_lshl_b64 s[42:43], s[22:23], 2
	v_add3_u32 v27, s70, v26, v119
	s_add_u32 s42, s26, s42
	v_add3_u32 v168, v27, v123, v129
	s_addc_u32 s43, s27, s43
	v_mov_b32_e32 v117, v115
	v_add_u32_e32 v27, 0x100, v164
	v_lshl_add_u64 v[126:127], s[42:43], 0, v[116:117]
	v_lshrrev_b32_e32 v117, 5, v27
	v_lshlrev_b32_e32 v27, 11, v117
	s_ashr_i32 s37, s36, 31
	v_add3_u32 v26, 0, v26, v119
	s_lshl_b64 s[36:37], s[36:37], 2
	v_add3_u32 v173, v26, v123, v129
	v_add3_u32 v26, 0, v27, v119
	s_add_u32 s36, s40, s36
	v_add3_u32 v174, v26, v123, v129
	v_lshlrev_b32_e32 v232, 2, v44
	v_and_b32_e32 v232, 48, v232
	v_xor_b32_e32 v233, 16, v232
	v_xor_b32_e32 v234, 32, v232
	v_xor_b32_e32 v235, 48, v232
	v_add_u32_e32 v224, v173, v232
	v_add_u32_e32 v225, v173, v233
	v_add_u32_e32 v226, v173, v234
	v_add_u32_e32 v227, v173, v235
	v_add_u32_e32 v228, 0x8000, v224
	v_add_u32_e32 v229, 0x8000, v225
	v_add_u32_e32 v230, 0x8000, v226
	v_add_u32_e32 v231, 0x8000, v227
	v_lshlrev_b32_e32 v26, 3, v44
	s_addc_u32 s37, s41, s37
	v_lshrrev_b32_e32 v171, 3, v166
	v_and_b32_e32 v128, 56, v26
	s_lshl_b64 s[40:41], s[22:23], 1
	v_add3_u32 v28, s70, v27, v119
	v_mul_u32_u24_e32 v26, 0x84, v128
	v_lshlrev_b32_e32 v27, 2, v171
	s_add_u32 s40, s16, s40
	v_lshl_add_u32 v176, v122, 2, s15
	v_add3_u32 v182, s15, v26, v27
	s_addc_u32 s41, s17, s41
	s_lshl_b32 s15, s20, 6
	v_or_b32_e32 v26, s15, v166
	s_addk_i32 s15, 0xff00
	v_add3_u32 v169, v28, v123, v129
	v_lshlrev_b32_e32 v28, 7, v167
	v_lshlrev_b32_e32 v114, 1, v122
	v_lshrrev_b32_e32 v183, 5, v26
	v_or_b32_e32 v26, s15, v166
	v_cmp_gt_u32_e64 s[6:7], 8, v45
	s_mov_b32 s45, 0
	v_cmp_eq_u32_e64 s[8:9], 0, v45
	v_add_u32_e32 v170, 64, v167
	v_add_u32_e32 v172, 0x50, v167
	v_add_u32_e32 v175, 0x60, v167
	v_add_u32_e32 v177, 0x70, v167
	v_mul_u32_u24_e32 v178, 0x84, v171
	v_or_b32_e32 v179, 8, v171
	v_or_b32_e32 v180, 16, v171
	v_or_b32_e32 v181, 24, v171
	v_lshl_add_u64 v[130:131], s[40:41], 0, v[114:115]
	v_lshrrev_b32_e32 v184, 5, v26
	v_lshl_or_b32 v185, s20, 2, v165
	s_mov_b32 s23, -4
	v_add_u32_e32 v186, v118, v28
	s_mov_b32 s49, s11
	s_mov_b32 s46, 0
	v_and_b32_e32 v246, 3, v166
	v_lshlrev_b32_e32 v246, 2, v246
	v_add_u32_e32 v246, 0x1b000, v246
	s_lshl_b32 s64, s20, 2
	s_add_i32 s64, s64, 0x1b000
	v_mov_b32_e32 v247, s64
	v_lshlrev_b32_e32 v245, 2, v166
	s_lshl_b32 s65, s20, 8
	s_add_i32 s65, s65, 0x1b100
	v_add_u32_e32 v245, s65, v245
	v_cmp_eq_u32_e32 vcc, 0, v166
	s_nop 1
	v_cndmask_b32_e32 v247, v245, v247, vcc
	s_branch .LBB0_726

.LBB0_831:
	v_readlane_b32 s28, v255, 5
	s_and_b64 vcc, exec, s[8:9]
	v_readlane_b32 s31, v255, 8
	v_readlane_b32 s29, v255, 6
	v_readlane_b32 s30, v255, 7
	s_cbranch_vccz .LBB0_834
	s_bfe_u32 s4, s44, 0x20006
	s_lshl_b32 s5, s4, 5
	s_add_i32 s5, s5, 0
	s_mul_i32 s6, s4, 0x1e0
	s_lshl_b32 s4, s4, 9
	v_lshl_add_u32 v110, v165, 2, s5
	s_add_i32 s5, s5, s6
	v_lshlrev_b32_e32 v2, 2, v166
	s_add_i32 s4, s4, 0
	v_add_u32_e32 v111, s5, v2
	s_add_i32 s4, s4, 0x13000
	s_waitcnt vmcnt(8)
	v_mov_b32_e32 v24, 0
	v_add_u32_e32 v112, 0xb000, v111
	v_add_u32_e32 v113, s4, v2
	s_mov_b32 s4, -4
	v_mov_b32_e32 v25, v24
	v_mov_b32_e32 v22, v24
	v_mov_b32_e32 v23, v24
	v_mov_b32_e32 v6, v24
	v_mov_b32_e32 v7, v24
	v_mov_b32_e32 v8, v24
	v_mov_b32_e32 v9, v24
	v_and_b32_e32 v246, 3, v166
	v_lshlrev_b32_e32 v246, 2, v246
	v_add_u32_e32 v246, 0x1b010, v246
	s_lshl_b32 s64, s20, 2
	s_add_i32 s64, s64, 0x1b000
	v_mov_b32_e32 v247, s64
	v_lshlrev_b32_e32 v245, 2, v166
	s_lshl_b32 s65, s20, 8
	s_add_i32 s65, s65, 0x1b100
	v_add_u32_e32 v245, s65, v245
	v_cmp_eq_u32_e32 vcc, 0, v166
	s_nop 1
	v_cndmask_b32_e32 v247, v245, v247, vcc
	s_lshr_b32 s58, s10, 2
	s_lshl_b32 s58, s58, 8
	s_add_u32 s56, s92, s58
	s_addc_u32 s57, s93, 0
	s_add_u32 s56, s56, 0x37800000
	s_addc_u32 s57, s57, 0
	s_movk_i32 s58, 0x2000
	s_mov_b32 s59, 0
	s_bitcmp1_b32 s10, 1
	s_cbranch_scc0 .Lw_fwd
	s_add_u32 s56, s56, 0x7ffe000
	s_addc_u32 s57, s57, 0
	s_mov_b32 s58, 0xffffe000
	s_mov_b32 s59, -1
